# rowpass loops: rows dealt to waves interleaved with stride 128 inside 128-wave groups (instead of 17 contiguous rows per wave), on top of merge epilogue rewrite
# baseline (speedup 1.0000x reference)
; #define PIN(i) (((KargTbl)__builtin_amdgcn_kernarg_segment_ptr())[i])
; DI int obid() { int t = blockIdx.x; asm volatile("" : "+s"(t)); return t; }
; DI int ogrid() { int t = gridDim.x; asm volatile("" : "+s"(t)); return t; }
; DI int otid() { int t = threadIdx.x; asm volatile("" : "+v"(t)); return t; }
; DI void phase_rowpass(unsigned char* ws, int nrows, const float* xin_lat, const float* xin_ctx, const float* y, const float* gate_base  ,
;                       const float* gpost, bool write_x, bool write_h, const float* hmod_base  , int sc_which, int sh_which, const float* gpre) {
;     const int lane = otid() & 63, wave = otid() >> 6;
;     float eps = EPS; asm volatile("" : "+v"(eps));
;     float* xout_lat = (float*)PIN(25); float* xout_ctx = (float*)(ws + WS_CTXRES);
;     bf16_t* H = (bf16_t*)(ws + WS_H);
;     const int nwv = ogrid() * 8, per = (nrows + nwv - 1) / nwv;
;     int r = (obid() * 8 + wave) * per;
;     const int rend = min(r + per, nrows);
;     f32x4 xv[4], yv[4], xnx[4], ynx[4];
;     f32x4 vgt[4], vgp[4], vpre[4], vsc[4], vsh[4];
; #pragma unroll
;     for (int i = 0; i < 4; ++i) { xv[i] = (f32x4){0.f, 0.f, 0.f, 0.f}; yv[i] = xv[i]; xnx[i] = xv[i]; ynx[i] = xv[i]; vgt[i] = xv[i]; vgp[i] = xv[i]; vpre[i] = xv[i]; vsc[i] = xv[i]; vsh[i] = xv[i]; }
;     if (r < rend) {
;         const float* xi = r < ML ? xin_lat + (size_t)r * 1024 : xin_ctx + (size_t)(r - ML) * 1024;
; #pragma unroll
;         for (int i = 0; i < 4; ++i) xv[i] = __builtin_nontemporal_load((const f32x4*)(xi + i * 256 + lane * 4));
;         if (y) {
; #pragma unroll
;             for (int i = 0; i < 4; ++i) yv[i] = __builtin_nontemporal_load((const f32x4*)(y + (size_t)r * 1024 + i * 256 + lane * 4));
;         }
; #pragma unroll
;         for (int i = 0; i < 4; ++i) { if (y) vgp[i] = *(const f32x4*)(gpost + i * 256 + lane * 4); if (write_h) vpre[i] = *(const f32x4*)(gpre + i * 256 + lane * 4); }
;     }
.LBB0_59:
	v_writelane_b32 v255, s18, 3
	s_andn2_b64 vcc, exec, s[14:15]
	s_nop 0
	v_writelane_b32 v255, s19, 4
	v_writelane_b32 v255, s31, 5
	s_cbranch_vccnz .LBB0_226
	s_add_u32 s2, s84, 0x800000
	s_addc_u32 s3, s85, 0
	v_writelane_b32 v255, s2, 6
	s_mov_b64 s[14:15], -1
	s_mov_b64 s[10:11], 0
	v_writelane_b32 v255, s3, 7
	s_cmp_lt_i32 s64, 1
	s_mov_b64 s[12:13], 0
	s_cbranch_scc1 .LBB0_75
	s_cmp_eq_u32 s64, 1
	s_mov_b64 s[12:13], -1
	s_cbranch_scc0 .LBB0_74
	v_mov_b32_e32 v22, v176
	v_mov_b32_e32 v0, v176
	v_mov_b32_e32 v90, 0x358637bd
	s_load_dwordx2 s[12:13], s[0:1], 0x0
	s_load_dwordx2 s[14:15], s[0:1], 0x10
	s_load_dwordx2 s[18:19], s[0:1], 0x30
	s_load_dwordx2 s[2:3], s[0:1], 0xc8
	s_waitcnt lgkmcnt(0)
	s_mov_b32 s2, s66
	s_lshl_b32 s2, s2, 3
	s_abs_i32 s3, s2
	v_cvt_f32_u32_e32 v2, s3
	s_add_i32 s4, s2, 0x87ff
	s_xor_b32 s5, s4, s2
	s_sub_i32 s2, 0xffff7801, s2
	v_rcp_iflag_f32_e32 v2, v2
	s_max_i32 s2, s4, s2
	s_sub_i32 s4, 0, s3
	s_ashr_i32 s5, s5, 31
	v_mul_f32_e32 v2, 0x4f7ffffe, v2
	v_cvt_u32_f32_e32 v2, v2
	v_ashrrev_i32_e32 v0, 6, v0
	v_readfirstlane_b32 s6, v2
	s_mul_i32 s4, s4, s6
	s_mul_hi_u32 s4, s6, s4
	s_add_i32 s6, s6, s4
	s_mul_hi_u32 s4, s2, s6
	s_mul_i32 s6, s4, s3
	s_sub_i32 s2, s2, s6
	s_add_i32 s6, s4, 1
	s_sub_i32 s7, s2, s3
	s_cmp_ge_u32 s2, s3
	s_cselect_b32 s4, s6, s4
	s_cselect_b32 s2, s7, s2
	s_add_i32 s6, s4, 1
	s_cmp_ge_u32 s2, s3
	s_cselect_b32 s2, s6, s4
	s_xor_b32 s2, s2, s5
	s_mov_b32 s3, s33
	s_sub_i32 s2, s2, s5
	s_nop 0
	v_lshl_add_u32 v0, s3, 3, v0
	v_lshrrev_b32_e32 v88, 7, v0
	v_and_b32_e32 v0, 0x7f, v0
	s_lshl_b32 s3, s2, 7
	v_mul_lo_u32 v88, v88, s3
	s_add_i32 s3, s3, 0xffffff81
	v_add_u32_e32 v88, v88, v0
	v_add_u32_e32 v0, s3, v88
	v_min_i32_e32 v91, 0x8800, v0
	v_cmp_lt_i32_e32 vcc, v88, v91
	s_and_saveexec_b64 s[16:17], vcc
	s_cbranch_execz .LBB0_73
	v_add_u32_e32 v0, 0xffff8000, v88
	v_cmp_gt_i32_e32 vcc, s63, v88
	v_mov_b32_e32 v4, s13
	v_ashrrev_i32_e32 v89, 31, v88
	v_cndmask_b32_e32 v2, v0, v88, vcc
	v_mov_b32_e32 v0, s15
	v_cndmask_b32_e32 v5, v0, v4, vcc
	v_mov_b32_e32 v0, s14
	v_mov_b32_e32 v4, s12
	v_cndmask_b32_e32 v3, 0, v89, vcc
	v_cndmask_b32_e32 v4, v0, v4, vcc
	v_lshlrev_b32_e32 v0, 2, v22
	v_lshlrev_b64 v[2:3], 12, v[2:3]
	v_and_b32_e32 v26, 0xfc, v0
	v_lshl_add_u64 v[2:3], v[4:5], 0, v[2:3]
	v_lshlrev_b32_e32 v0, 2, v26
	v_lshl_add_u64 v[2:3], v[2:3], 0, v[0:1]
	global_load_dwordx4 v[78:81], v[2:3], off nt
	global_load_dwordx4 v[74:77], v[2:3], off offset:1024 nt
	global_load_dwordx4 v[62:65], v[2:3], off offset:2048 nt
	global_load_dwordx4 v[18:21], v[2:3], off offset:3072 nt
	s_nop 0
	global_load_dwordx4 v[2:5], v0, s[18:19]
	global_load_dwordx4 v[6:9], v0, s[18:19] offset:1024
	global_load_dwordx4 v[10:13], v0, s[18:19] offset:2048
	global_load_dwordx4 v[14:17], v0, s[18:19] offset:3072
	v_readlane_b32 s2, v255, 6
	v_readlane_b32 s3, v255, 7
	v_lshlrev_b64 v[24:25], 11, v[88:89]
	v_mov_b32_e32 v23, v1
	v_lshl_add_u64 v[82:83], s[2:3], 0, v[0:1]
	v_and_b32_e32 v0, 63, v22
	v_readlane_b32 s2, v254, 53
	v_lshl_or_b32 v24, v0, 3, v24
	v_readlane_b32 s3, v254, 54
	v_mov_b32_e32 v22, v1
	v_lshlrev_b32_e32 v0, 2, v26
	v_lshl_add_u64 v[84:85], s[2:3], 0, v[24:25]
	v_mov_b32_e32 v24, v1
	v_mov_b32_e32 v25, v1
	v_mov_b64_e32 v[44:45], v[24:25]
	v_mov_b64_e32 v[48:49], v[24:25]
	v_mov_b64_e32 v[52:53], v[24:25]
	v_mov_b64_e32 v[40:41], v[24:25]
	v_mov_b64_e32 v[36:37], v[24:25]
	v_mov_b64_e32 v[32:33], v[24:25]
	v_mov_b64_e32 v[28:29], v[24:25]
	v_mov_b64_e32 v[68:69], v[24:25]
	v_mov_b64_e32 v[72:73], v[24:25]
	v_mov_b64_e32 v[56:57], v[24:25]
	v_mov_b64_e32 v[60:61], v[24:25]
	v_mov_b32_e32 v92, -1
	s_mov_b64 s[18:19], 0
	v_mov_b64_e32 v[42:43], v[22:23]
	v_mov_b64_e32 v[46:47], v[22:23]
	v_mov_b64_e32 v[50:51], v[22:23]
	v_mov_b64_e32 v[38:39], v[22:23]
	v_mov_b64_e32 v[34:35], v[22:23]
	v_mov_b64_e32 v[30:31], v[22:23]
	v_mov_b64_e32 v[26:27], v[22:23]
	v_mov_b64_e32 v[66:67], v[22:23]
	v_mov_b64_e32 v[70:71], v[22:23]
	v_mov_b64_e32 v[54:55], v[22:23]
	v_mov_b64_e32 v[58:59], v[22:23]
	s_branch .LBB0_65
; DI unsigned pk_bf16(float lo, float hi) { unsigned r; asm("v_cvt_pk_bf16_f32 %0, %1, %2" : "=v"(r) : "v"(lo), "v"(hi)); return r; }
; DI void phase_rowpass(unsigned char* ws, int nrows, const float* xin_lat, const float* xin_ctx, const float* y, const float* gate_base  ,
;                       const float* gpost, bool write_x, bool write_h, const float* hmod_base  , int sc_which, int sh_which, const float* gpre) {
;     ...
;     for (; r < rend; ++r) {
;         const int mi = r < ML ? (r >> 12) : 8;
;         const int rn = r + 1;
;         if (rn < rend) {
;             const float* xi = rn < ML ? xin_lat + (size_t)rn * 1024 : xin_ctx + (size_t)(rn - ML) * 1024;
; #pragma unroll
;             for (int i = 0; i < 4; ++i) xnx[i] = __builtin_nontemporal_load((const f32x4*)(xi + i * 256 + lane * 4));
;             if (y) {
; #pragma unroll
;                 for (int i = 0; i < 4; ++i) ynx[i] = __builtin_nontemporal_load((const f32x4*)(y + (size_t)rn * 1024 + i * 256 + lane * 4));
;             }
;         }
;     ...
;         if (write_h) {
;             float ss = 0.f;
; #pragma unroll
;             for (int i = 0; i < 4; ++i) ss += xv[i][0] * xv[i][0] + xv[i][1] * xv[i][1] + xv[i][2] * xv[i][2] + xv[i][3] * xv[i][3];
;             ss = wave_sum(ss);
;             const float rs = rsqrtf(ss * (1.f / 1024.f) + eps);
; #pragma unroll
;             for (int i = 0; i < 4; ++i) {
;                 float hv[4];
; #pragma unroll
;                 for (int j = 0; j < 4; ++j) hv[j] = (xv[i][j] * rs * vpre[i][j]) * (1.f + vsc[i][j]) + vsh[i][j];
;                 u32x2 o; o[0] = pk_bf16(hv[0], hv[1]); o[1] = pk_bf16(hv[2], hv[3]);
;                 *(u32x2*)(H + (size_t)r * 1024 + i * 256 + lane * 4) = o;
;             }
;         }
; #pragma unroll
;         for (int i = 0; i < 4; ++i) { xv[i] = xnx[i]; yv[i] = ynx[i]; }
.LBB0_64:
	s_or_b64 exec, exec, s[42:43]
	s_waitcnt vmcnt(0)
	v_pk_mul_f32 v[104:105], v[78:79], v[78:79]
	v_pk_mul_f32 v[106:107], v[74:75], v[74:75]
	v_pk_mul_f32 v[100:101], v[80:81], v[80:81]
	v_pk_mul_f32 v[102:103], v[76:77], v[76:77]
	v_mov_b32_e32 v108, v104
	v_mov_b32_e32 v109, v106
	v_mov_b32_e32 v106, v105
	v_pk_add_f32 v[104:105], v[108:109], v[106:107]
	v_mov_b32_e32 v106, v100
	v_mov_b32_e32 v107, v102
	v_pk_mul_f32 v[96:97], v[18:19], v[18:19]
	v_pk_mul_f32 v[98:99], v[62:63], v[62:63]
	v_pk_add_f32 v[104:105], v[106:107], v[104:105]
	v_mov_b32_e32 v102, v101
	v_pk_mul_f32 v[88:89], v[20:21], v[20:21]
	v_pk_mul_f32 v[94:95], v[64:65], v[64:65]
	v_pk_add_f32 v[100:101], v[102:103], v[104:105]
	v_mov_b32_e32 v102, v96
	v_mov_b32_e32 v103, v98
	v_mov_b32_e32 v98, v97
	v_pk_add_f32 v[96:97], v[102:103], v[98:99]
	v_mov_b32_e32 v98, v88
	v_mov_b32_e32 v99, v94
	v_pk_add_f32 v[96:97], v[98:99], v[96:97]
	v_mov_b32_e32 v94, v89
	v_pk_add_f32 v[88:89], v[94:95], v[96:97]
	v_add_f32_e32 v93, v100, v101
	v_add_f32_e32 v89, v89, v93
	v_add_f32_e32 v88, v88, v89
	v_mov_b32_e32 v89, v176
	s_and_b64 s[2:3], exec, s[40:41]
	v_lshlrev_b32_e32 v89, 2, v89
	v_bitop3_b32 v93, v89, s80, v178 bitop3:0x6c
	ds_bpermute_b32 v93, v93, v88
	s_or_b64 s[18:19], s[2:3], s[18:19]
	s_mov_b64 s[2:3], 0x40000
	s_waitcnt lgkmcnt(0)
	v_add_f32_e32 v88, v88, v93
	v_bitop3_b32 v93, v89, 64, v178 bitop3:0x6c
	ds_bpermute_b32 v93, v93, v88
	s_waitcnt lgkmcnt(0)
	v_add_f32_e32 v88, v88, v93
	v_bitop3_b32 v93, v89, 32, v178 bitop3:0x6c
	ds_bpermute_b32 v93, v93, v88
	s_waitcnt lgkmcnt(0)
	v_add_f32_e32 v88, v88, v93
	v_bitop3_b32 v93, v89, 16, v178 bitop3:0x6c
	ds_bpermute_b32 v93, v93, v88
	s_waitcnt lgkmcnt(0)
	v_add_f32_e32 v88, v88, v93
	v_bitop3_b32 v93, v89, 8, v178 bitop3:0x6c
	ds_bpermute_b32 v93, v93, v88
	v_bitop3_b32 v89, v89, 4, v178 bitop3:0x6c
	s_waitcnt lgkmcnt(0)
	v_add_f32_e32 v88, v88, v93
	ds_bpermute_b32 v89, v89, v88
	s_waitcnt lgkmcnt(0)
	v_add_f32_e32 v88, v88, v89
	v_fmamk_f32 v88, v88, 0x3a800000, v90
	v_cmp_gt_f32_e32 vcc, s60, v88
	v_mul_f32_e32 v89, 0x4b800000, v88
	s_nop 0
	v_cndmask_b32_e32 v88, v88, v89, vcc
	v_rsq_f32_e32 v88, v88
	s_nop 0
	v_mul_f32_e32 v89, 0x45800000, v88
	v_cndmask_b32_e32 v88, v88, v89, vcc
	v_mul_f32_e32 v78, v78, v88
	v_mul_f32_e32 v78, v2, v78
	v_add_f32_e32 v89, 1.0, v26
	v_mul_f32_e32 v79, v79, v88
	v_fma_f32 v78, v89, v78, v58
	v_mul_f32_e32 v79, v3, v79
	v_add_f32_e32 v89, 1.0, v27
	v_mul_f32_e32 v80, v80, v88
	v_fma_f32 v79, v89, v79, v59
	v_mul_f32_e32 v80, v4, v80
	v_add_f32_e32 v89, 1.0, v28
	v_mul_f32_e32 v81, v81, v88
	v_fma_f32 v80, v89, v80, v60
	v_mul_f32_e32 v81, v5, v81
	v_add_f32_e32 v89, 1.0, v29
	v_cvt_pk_bf16_f32 v78, v78, v79
	v_mul_f32_e32 v74, v74, v88
	v_fma_f32 v81, v89, v81, v61
	v_cvt_pk_bf16_f32 v79, v80, v81
	flat_store_dwordx2 v[84:85], v[78:79]
	v_mul_f32_e32 v74, v6, v74
	v_add_f32_e32 v78, 1.0, v30
	v_mul_f32_e32 v75, v75, v88
	v_fma_f32 v74, v78, v74, v54
	v_mul_f32_e32 v75, v7, v75
	v_add_f32_e32 v78, 1.0, v31
	v_mul_f32_e32 v76, v76, v88
	v_fma_f32 v75, v78, v75, v55
	v_mul_f32_e32 v76, v8, v76
	v_add_f32_e32 v78, 1.0, v32
	v_mul_f32_e32 v77, v77, v88
	v_fma_f32 v76, v78, v76, v56
	v_mul_f32_e32 v77, v9, v77
	v_add_f32_e32 v78, 1.0, v33
	v_cvt_pk_bf16_f32 v74, v74, v75
	v_mul_f32_e32 v62, v62, v88
	v_fma_f32 v77, v78, v77, v57
	v_cvt_pk_bf16_f32 v75, v76, v77
	flat_store_dwordx2 v[84:85], v[74:75] offset:512
	v_mul_f32_e32 v62, v10, v62
	v_add_f32_e32 v74, 1.0, v34
	v_mul_f32_e32 v63, v63, v88
	v_fma_f32 v62, v74, v62, v70
	v_mul_f32_e32 v63, v11, v63
	v_add_f32_e32 v74, 1.0, v35
	v_mul_f32_e32 v64, v64, v88
	v_fma_f32 v63, v74, v63, v71
	v_mul_f32_e32 v64, v12, v64
	v_add_f32_e32 v74, 1.0, v36
	v_mul_f32_e32 v65, v65, v88
	v_fma_f32 v64, v74, v64, v72
	v_mul_f32_e32 v65, v13, v65
	v_add_f32_e32 v74, 1.0, v37
	v_cvt_pk_bf16_f32 v62, v62, v63
	v_mul_f32_e32 v18, v18, v88
	v_fma_f32 v65, v74, v65, v73
	v_cvt_pk_bf16_f32 v63, v64, v65
	flat_store_dwordx2 v[84:85], v[62:63] offset:1024
	v_mul_f32_e32 v18, v14, v18
	v_add_f32_e32 v62, 1.0, v38
	v_mul_f32_e32 v19, v19, v88
	v_fma_f32 v18, v62, v18, v66
	v_mul_f32_e32 v19, v15, v19
	v_add_f32_e32 v62, 1.0, v39
	v_mul_f32_e32 v20, v20, v88
	v_fma_f32 v19, v62, v19, v67
	v_mul_f32_e32 v20, v16, v20
	v_add_f32_e32 v62, 1.0, v40
	v_mul_f32_e32 v21, v21, v88
	v_fma_f32 v20, v62, v20, v68
	v_mul_f32_e32 v21, v17, v21
	v_add_f32_e32 v62, 1.0, v41
	v_fma_f32 v21, v62, v21, v69
	v_cvt_pk_bf16_f32 v18, v18, v19
	v_cvt_pk_bf16_f32 v19, v20, v21
	flat_store_dwordx2 v[84:85], v[18:19] offset:1536
	v_lshl_add_u64 v[84:85], v[84:85], 0, s[2:3]
	v_mov_b64_e32 v[88:89], v[86:87]
	v_mov_b32_e32 v78, v50
	v_mov_b32_e32 v79, v51
	v_mov_b32_e32 v80, v52
	v_mov_b32_e32 v81, v53
	v_mov_b32_e32 v74, v46
	v_mov_b32_e32 v75, v47
	v_mov_b32_e32 v76, v48
	v_mov_b32_e32 v77, v49
	v_mov_b32_e32 v62, v42
	v_mov_b32_e32 v63, v43
	v_mov_b32_e32 v64, v44
	v_mov_b32_e32 v65, v45
	v_mov_b32_e32 v18, v22
	v_mov_b32_e32 v19, v23
	v_mov_b32_e32 v20, v24
	v_mov_b32_e32 v21, v25
	s_andn2_b64 exec, exec, s[18:19]
	s_cbranch_execz .LBB0_73
.LBB0_65:
	v_lshl_add_u64 v[86:87], v[88:89], 0, s[82:83]
	v_cmp_lt_i32_e32 vcc, v86, v91
	v_cmp_ge_i32_e64 s[40:41], v86, v91
	s_and_saveexec_b64 s[42:43], vcc
	s_cbranch_execz .LBB0_67
	v_add_u32_e32 v22, 0xffff8080, v88
	v_cmp_gt_i32_e32 vcc, 0x7f80, v88
	v_mov_b32_e32 v24, s15
	v_mov_b32_e32 v25, s13
	v_cndmask_b32_e32 v23, 0, v87, vcc
	v_cndmask_b32_e32 v22, v22, v86, vcc
	v_cndmask_b32_e32 v25, v24, v25, vcc
	v_mov_b32_e32 v24, s14
	v_mov_b32_e32 v42, s12
	v_cndmask_b32_e32 v24, v24, v42, vcc
	v_lshlrev_b64 v[22:23], 12, v[22:23]
	v_lshl_add_u64 v[22:23], v[24:25], 0, v[22:23]
	v_lshl_add_u64 v[22:23], v[22:23], 0, v[0:1]
	global_load_dwordx4 v[50:53], v[22:23], off nt
	global_load_dwordx4 v[46:49], v[22:23], off offset:1024 nt
	global_load_dwordx4 v[42:45], v[22:23], off offset:2048 nt
	s_nop 0
	global_load_dwordx4 v[22:25], v[22:23], off offset:3072 nt

; DI int obid() { int t = blockIdx.x; asm volatile("" : "+s"(t)); return t; }
; DI int ogrid() { int t = gridDim.x; asm volatile("" : "+s"(t)); return t; }
; DI void phase_rowpass(unsigned char* ws, int nrows, const float* xin_lat, const float* xin_ctx, const float* y, const float* gate_base  ,
;                       const float* gpost, bool write_x, bool write_h, const float* hmod_base  , int sc_which, int sh_which, const float* gpre) {
;     ...
;     const int nwv = ogrid() * 8, per = (nrows + nwv - 1) / nwv;
;     int r = (obid() * 8 + wave) * per;
;     const int rend = min(r + per, nrows);
;     f32x4 xv[4], yv[4], xnx[4], ynx[4];
;     f32x4 vgt[4], vgp[4], vpre[4], vsc[4], vsh[4];
; #pragma unroll
;     for (int i = 0; i < 4; ++i) { xv[i] = (f32x4){0.f, 0.f, 0.f, 0.f}; yv[i] = xv[i]; xnx[i] = xv[i]; ynx[i] = xv[i]; vgt[i] = xv[i]; vgp[i] = xv[i]; vpre[i] = xv[i]; vsc[i] = xv[i]; vsh[i] = xv[i]; }
;     if (r < rend) {
;         const float* xi = r < ML ? xin_lat + (size_t)r * 1024 : xin_ctx + (size_t)(r - ML) * 1024;
; #pragma unroll
;         for (int i = 0; i < 4; ++i) xv[i] = __builtin_nontemporal_load((const f32x4*)(xi + i * 256 + lane * 4));
;         if (y) {
; #pragma unroll
;             for (int i = 0; i < 4; ++i) yv[i] = __builtin_nontemporal_load((const f32x4*)(y + (size_t)r * 1024 + i * 256 + lane * 4));
;         }
; #pragma unroll
;         for (int i = 0; i < 4; ++i) { if (y) vgp[i] = *(const f32x4*)(gpost + i * 256 + lane * 4); if (write_h) vpre[i] = *(const f32x4*)(gpre + i * 256 + lane * 4); }
;     }
.LBB0_102:
	v_mov_b32_e32 v2, v176
	v_mov_b32_e32 v0, v176
	v_mov_b32_e32 v141, 0x358637bd
	s_mov_b32 s2, s66
	s_load_dwordx2 s[40:41], s[0:1], 0x38
	s_load_dwordx2 s[44:45], s[0:1], 0x40
	s_load_dwordx2 s[18:19], s[0:1], 0xc8
	s_lshl_b32 s2, s2, 3
	s_abs_i32 s3, s2
	v_cvt_f32_u32_e32 v3, s3
	s_sub_i32 s5, 0, s3
	s_add_i32 s4, s9, s2
	s_add_i32 s4, s4, -1
	v_rcp_iflag_f32_e32 v3, v3
	s_xor_b32 s2, s4, s2
	s_abs_i32 s4, s4
	s_ashr_i32 s2, s2, 31
	v_mul_f32_e32 v3, 0x4f7ffffe, v3
	v_cvt_u32_f32_e32 v3, v3
	v_ashrrev_i32_e32 v0, 6, v0
	v_readfirstlane_b32 s6, v3
	s_mul_i32 s5, s5, s6
	s_mul_hi_u32 s5, s6, s5
	s_add_i32 s6, s6, s5
	s_mul_hi_u32 s5, s4, s6
	s_mul_i32 s6, s5, s3
	s_sub_i32 s4, s4, s6
	s_add_i32 s6, s5, 1
	s_sub_i32 s7, s4, s3
	s_cmp_ge_u32 s4, s3
	s_cselect_b32 s5, s6, s5
	s_cselect_b32 s4, s7, s4
	s_add_i32 s6, s5, 1
	s_cmp_ge_u32 s4, s3
	s_cselect_b32 s3, s6, s5
	s_xor_b32 s3, s3, s2
	s_sub_i32 s2, s3, s2
	s_mov_b32 s3, s33
	s_nop 0
	v_lshl_add_u32 v0, s3, 3, v0
	v_lshrrev_b32_e32 v144, 7, v0
	v_and_b32_e32 v0, 0x7f, v0
	s_lshl_b32 s3, s2, 7
	v_mul_lo_u32 v144, v144, s3
	s_add_i32 s3, s3, 0xffffff81
	v_add_u32_e32 v144, v144, v0
	v_add_u32_e32 v0, s3, v144
	v_min_i32_e32 v164, s9, v0
	v_cmp_lt_i32_e32 vcc, v144, v164
	s_and_saveexec_b64 s[42:43], vcc
	s_cbranch_execz .LBB0_113
	v_add_u32_e32 v0, 0xffff8000, v144
	v_cmp_gt_i32_e32 vcc, s63, v144
	v_readlane_b32 s2, v255, 3
	s_waitcnt lgkmcnt(0)
	v_mov_b32_e32 v3, s15
	v_cndmask_b32_e32 v4, v0, v144, vcc
	v_mov_b32_e32 v0, s17
	v_readlane_b32 s3, v255, 4
	s_lshl_b32 s72, s2, 10
	v_ashrrev_i32_e32 v145, 31, v144
	v_cndmask_b32_e32 v7, v0, v3, vcc
	v_mov_b32_e32 v0, s16
	v_mov_b32_e32 v3, s14
	s_lshl_b64 s[2:3], s[72:73], 2
	v_cndmask_b32_e32 v5, 0, v145, vcc
	v_cndmask_b32_e32 v6, v0, v3, vcc
	v_lshlrev_b32_e32 v0, 2, v2
	s_add_u32 s4, s44, s2
	v_lshlrev_b64 v[4:5], 12, v[4:5]
	v_and_b32_e32 v140, 0xfc, v0
	s_addc_u32 s5, s45, s3
	v_lshl_add_u64 v[4:5], v[6:7], 0, v[4:5]
	v_lshlrev_b32_e32 v0, 2, v140
	s_add_u32 s2, s40, s2
	v_lshl_add_u64 v[20:21], v[4:5], 0, v[0:1]
	v_lshlrev_b64 v[142:143], 12, v[144:145]
	s_addc_u32 s3, s41, s3
	flat_load_dwordx4 v[124:127], v[20:21] nt
	global_load_dwordx4 v[4:7], v0, s[2:3] offset:3072
	global_load_dwordx4 v[8:11], v0, s[2:3] offset:2048
	global_load_dwordx4 v[12:15], v0, s[2:3]
	global_load_dwordx4 v[16:19], v0, s[2:3] offset:1024
	flat_load_dwordx4 v[166:169], v[20:21] offset:1024 nt
	flat_load_dwordx4 v[120:123], v[20:21] offset:2048 nt
	flat_load_dwordx4 v[170:173], v[20:21] offset:3072 nt
	v_lshl_add_u64 v[20:21], s[76:77], 0, v[142:143]
	v_lshl_add_u64 v[20:21], v[20:21], 0, v[0:1]
	flat_load_dwordx4 v[132:135], v[20:21] nt
	flat_load_dwordx4 v[128:131], v[20:21] offset:1024 nt
	flat_load_dwordx4 v[116:119], v[20:21] offset:2048 nt
	flat_load_dwordx4 v[136:139], v[20:21] offset:3072 nt
	s_nop 0
	global_load_dwordx4 v[20:23], v0, s[4:5]
	global_load_dwordx4 v[24:27], v0, s[4:5] offset:1024
	global_load_dwordx4 v[28:31], v0, s[4:5] offset:2048
	global_load_dwordx4 v[32:35], v0, s[4:5] offset:3072
	v_lshl_add_u64 v[146:147], s[10:11], 0, v[0:1]
	s_mov_b64 s[2:3], 0x2000
	v_lshl_add_u64 v[148:149], v[146:147], 0, s[2:3]
	v_readlane_b32 s2, v254, 53
	v_and_b32_e32 v36, 63, v2
	v_lshlrev_b32_e32 v0, 1, v140
	v_readlane_b32 s3, v254, 54
	v_mov_b32_e32 v2, v1
	v_mov_b32_e32 v3, v1
	v_lshl_add_u64 v[150:151], s[2:3], 0, v[0:1]
	v_lshlrev_b32_e32 v0, 4, v36
	v_lshl_add_u64 v[152:153], s[84:85], 0, v[0:1]
	v_mov_b32_e32 v0, v1
	v_mov_b64_e32 v[38:39], v[2:3]
	v_mov_b64_e32 v[42:43], v[2:3]
	v_mov_b64_e32 v[46:47], v[2:3]
	v_mov_b64_e32 v[50:51], v[2:3]
	v_mov_b64_e32 v[62:63], v[2:3]
	v_mov_b64_e32 v[66:67], v[2:3]
	v_mov_b64_e32 v[70:71], v[2:3]
	v_mov_b64_e32 v[74:75], v[2:3]
	v_mov_b64_e32 v[82:83], v[2:3]
	v_mov_b64_e32 v[78:79], v[2:3]
	v_mov_b64_e32 v[58:59], v[2:3]
	v_mov_b64_e32 v[54:55], v[2:3]
	v_mov_b64_e32 v[94:95], v[2:3]
	v_mov_b64_e32 v[98:99], v[2:3]
	v_mov_b64_e32 v[86:87], v[2:3]
	v_mov_b64_e32 v[90:91], v[2:3]
	v_mov_b64_e32 v[110:111], v[2:3]
	v_mov_b64_e32 v[114:115], v[2:3]
	v_mov_b64_e32 v[102:103], v[2:3]
	v_mov_b64_e32 v[106:107], v[2:3]
	v_mov_b32_e32 v165, -1
	s_mov_b64 s[44:45], 0
	v_mov_b64_e32 v[36:37], v[0:1]
	v_mov_b64_e32 v[40:41], v[0:1]
	v_mov_b64_e32 v[44:45], v[0:1]
	v_mov_b64_e32 v[48:49], v[0:1]
	v_mov_b64_e32 v[60:61], v[0:1]
	v_mov_b64_e32 v[64:65], v[0:1]
	v_mov_b64_e32 v[68:69], v[0:1]
	v_mov_b64_e32 v[72:73], v[0:1]
	v_mov_b64_e32 v[80:81], v[0:1]
	v_mov_b64_e32 v[76:77], v[0:1]
	v_mov_b64_e32 v[56:57], v[0:1]
	v_mov_b64_e32 v[52:53], v[0:1]
	v_mov_b64_e32 v[92:93], v[0:1]
	v_mov_b64_e32 v[96:97], v[0:1]
	v_mov_b64_e32 v[84:85], v[0:1]
	v_mov_b64_e32 v[88:89], v[0:1]
	v_mov_b64_e32 v[108:109], v[0:1]
	v_mov_b64_e32 v[112:113], v[0:1]
	v_mov_b64_e32 v[100:101], v[0:1]
	v_mov_b64_e32 v[104:105], v[0:1]
	s_waitcnt vmcnt(0) lgkmcnt(0)
	v_mov_b32_e32 v160, v125
	v_mov_b32_e32 v2, v7
	v_mov_b32_e32 v3, v11
	v_mov_b32_e32 v7, v10
	v_mov_b32_e32 v10, v4
	v_mov_b32_e32 v11, v8
	v_mov_b32_e32 v8, v5
	v_mov_b32_e32 v4, v15
	v_mov_b32_e32 v5, v19
	v_mov_b32_e32 v15, v18
	v_mov_b32_e32 v18, v12
	v_mov_b32_e32 v19, v16
	v_mov_b32_e32 v16, v13
	v_mov_b32_e32 v156, v127
	v_mov_b32_e32 v125, v166
	v_mov_b32_e32 v161, v167
	v_mov_b32_e32 v127, v168
	v_mov_b32_e32 v157, v169
	v_mov_b32_e32 v159, v120
	v_mov_b32_e32 v155, v122
	v_mov_b32_e32 v158, v170
	v_mov_b32_e32 v120, v171
	v_mov_b32_e32 v154, v172
	v_mov_b32_e32 v122, v173
	s_branch .LBB0_105
; DI void phase_rowpass(unsigned char* ws, int nrows, const float* xin_lat, const float* xin_ctx, const float* y, const float* gate_base  ,
;                       const float* gpost, bool write_x, bool write_h, const float* hmod_base  , int sc_which, int sh_which, const float* gpre) {
;     ...
;         if (y) {
;             float ss = 0.f;
; #pragma unroll
;             for (int i = 0; i < 4; ++i) ss += yv[i][0] * yv[i][0] + yv[i][1] * yv[i][1] + yv[i][2] * yv[i][2] + yv[i][3] * yv[i][3];
;             ss = wave_sum(ss);
;             const float rs = rsqrtf(ss * (1.f / 1024.f) + eps);
; #pragma unroll
;             for (int i = 0; i < 4; ++i)
; #pragma unroll
;                 for (int j = 0; j < 4; ++j) xv[i][j] += vgt[i][j] * (yv[i][j] * rs * vgp[i][j]);
;         }
;         if (write_x) {
;             float* xo = r < ML ? xout_lat + (size_t)r * 1024 : xout_ctx + (size_t)(r - ML) * 1024;
; #pragma unroll
;             for (int i = 0; i < 4; ++i) __builtin_nontemporal_store(xv[i], (f32x4*)(xo + i * 256 + lane * 4));
;         }
;         if (write_h) {
;             float ss = 0.f;
; #pragma unroll
;             for (int i = 0; i < 4; ++i) ss += xv[i][0] * xv[i][0] + xv[i][1] * xv[i][1] + xv[i][2] * xv[i][2] + xv[i][3] * xv[i][3];
;             ss = wave_sum(ss);
;             const float rs = rsqrtf(ss * (1.f / 1024.f) + eps);
.LBB0_104:
	s_or_b64 exec, exec, s[20:21]
	s_waitcnt lgkmcnt(0)
	v_add_f32_e32 v166, v166, v167
	v_fmamk_f32 v166, v166, 0x3a800000, v141
	v_cmp_gt_f32_e32 vcc, s60, v166
	v_mul_f32_e32 v167, 0x4b800000, v166
	v_mov_b32_e32 v169, v128
	v_cndmask_b32_e32 v166, v166, v167, vcc
	v_rsq_f32_e32 v166, v166
	v_mov_b32_e32 v128, v133
	v_mov_b32_e32 v168, v132
	s_waitcnt vmcnt(0)
	v_mov_b32_e32 v132, v53
	v_mul_f32_e32 v167, 0x45800000, v166
	v_cndmask_b32_e32 v166, v166, v167, vcc
	v_pk_mul_f32 v[128:129], v[128:129], v[166:167] op_sel_hi:[1,0]
	v_mov_b32_e32 v133, v57
	v_pk_mul_f32 v[128:129], v[16:17], v[128:129]
	v_pk_mul_f32 v[116:117], v[116:117], v[166:167] op_sel_hi:[1,0]
	v_pk_fma_f32 v[128:129], v[132:133], v[128:129], v[160:161]
	v_mov_b32_e32 v132, v134
	v_mov_b32_e32 v133, v130
	v_pk_mul_f32 v[132:133], v[132:133], v[166:167] op_sel_hi:[1,0]
	v_mov_b32_e32 v130, v135
	v_pk_mul_f32 v[132:133], v[14:15], v[132:133]
	v_mov_b32_e32 v160, v54
	v_mov_b32_e32 v161, v58
	v_pk_mul_f32 v[130:131], v[130:131], v[166:167] op_sel_hi:[1,0]
	v_pk_fma_f32 v[126:127], v[160:161], v[132:133], v[126:127]
	v_pk_mul_f32 v[130:131], v[4:5], v[130:131]
	v_mov_b32_e32 v132, v55
	v_mov_b32_e32 v133, v59
	v_pk_fma_f32 v[130:131], v[132:133], v[130:131], v[156:157]
	v_pk_mul_f32 v[132:133], v[162:163], v[166:167] op_sel_hi:[1,0]
	v_mov_b32_e32 v134, v80
	v_pk_mul_f32 v[132:133], v[10:11], v[132:133]
	v_mov_b32_e32 v135, v76
	v_pk_fma_f32 v[132:133], v[134:135], v[132:133], v[158:159]
	v_pk_mul_f32 v[116:117], v[8:9], v[116:117]
	v_mov_b32_e32 v134, v81
	v_mov_b32_e32 v135, v77
	v_pk_fma_f32 v[120:121], v[134:135], v[116:117], v[120:121]
	v_pk_mul_f32 v[116:117], v[136:137], v[166:167] op_sel_hi:[1,0]
	v_pk_mul_f32 v[168:169], v[168:169], v[166:167] op_sel_hi:[1,0]
	v_pk_mul_f32 v[116:117], v[6:7], v[116:117]
	v_mov_b32_e32 v134, v82
	v_mov_b32_e32 v135, v78
	v_pk_mul_f32 v[168:169], v[18:19], v[168:169]
	v_mov_b32_e32 v170, v52
	v_mov_b32_e32 v171, v56
	v_pk_fma_f32 v[134:135], v[134:135], v[116:117], v[154:155]
	v_pk_mul_f32 v[116:117], v[118:119], v[166:167] op_sel_hi:[1,0]
	v_pk_fma_f32 v[124:125], v[170:171], v[168:169], v[124:125]
	v_pk_mul_f32 v[116:117], v[2:3], v[116:117]
	v_mov_b32_e32 v118, v83
	v_mov_b32_e32 v119, v79
	v_pk_fma_f32 v[122:123], v[118:119], v[116:117], v[122:123]
	v_lshl_add_u64 v[136:137], v[138:139], 0, v[0:1]
	v_mov_b32_e32 v116, v124
	v_mov_b32_e32 v117, v128
	v_mov_b32_e32 v118, v126
	v_mov_b32_e32 v119, v130
	flat_store_dwordx4 v[136:137], v[116:119] nt
	s_and_b64 s[2:3], exec, s[40:41]
	s_or_b64 s[44:45], s[2:3], s[44:45]
	v_mov_b32_e32 v116, v125
	v_mov_b32_e32 v117, v129
	v_mov_b32_e32 v118, v127
	v_mov_b32_e32 v119, v131
	flat_store_dwordx4 v[136:137], v[116:119] offset:1024 nt
	s_add_u32 s18, s18, 0x80000
	s_mov_b64 s[2:3], 0x80000
	v_mov_b32_e32 v116, v133
	v_mov_b32_e32 v117, v121
	v_mov_b32_e32 v118, v135
	v_mov_b32_e32 v119, v123
	flat_store_dwordx4 v[136:137], v[116:119] offset:2048 nt
	s_addc_u32 s19, s19, 0
	v_lshl_add_u64 v[152:153], v[152:153], 0, s[2:3]
	v_mov_b32_e32 v116, v132
	v_mov_b32_e32 v117, v120
	v_mov_b32_e32 v118, v134
	v_mov_b32_e32 v119, v122
	flat_store_dwordx4 v[136:137], v[116:119] offset:3072 nt
	v_mov_b64_e32 v[138:139], v[62:63]
	v_mov_b64_e32 v[136:137], v[60:61]
	v_pk_mul_f32 v[116:117], v[128:129], v[128:129]
	v_pk_mul_f32 v[118:119], v[120:121], v[120:121]
	v_pk_fma_f32 v[116:117], v[124:125], v[124:125], v[116:117]
	v_pk_fma_f32 v[118:119], v[132:133], v[132:133], v[118:119]
	v_pk_fma_f32 v[116:117], v[126:127], v[126:127], v[116:117]
	v_pk_fma_f32 v[118:119], v[134:135], v[134:135], v[118:119]
	v_pk_fma_f32 v[116:117], v[130:131], v[130:131], v[116:117]
	v_pk_fma_f32 v[118:119], v[122:123], v[122:123], v[118:119]
	v_add_f32_e32 v0, v116, v117
	v_mov_b32_e32 v116, v176
	v_add_f32_e32 v0, v119, v0
	v_lshlrev_b32_e32 v116, 2, v116
	v_add_f32_e32 v0, v118, v0
	v_bitop3_b32 v117, v116, s80, v178 bitop3:0x6c
	ds_bpermute_b32 v117, v117, v0
	v_add_f32_e32 v119, 1.0, v88
	v_mov_b32_e32 v160, v49
	v_mov_b32_e32 v156, v51
	v_mov_b32_e32 v161, v45
	s_waitcnt lgkmcnt(0)
	v_add_f32_e32 v0, v0, v117
	v_bitop3_b32 v117, v116, 64, v178 bitop3:0x6c
	ds_bpermute_b32 v117, v117, v0
	v_mov_b32_e32 v157, v47
	v_mov_b32_e32 v159, v40
	v_mov_b32_e32 v155, v42
	v_mov_b32_e32 v158, v36
	s_waitcnt lgkmcnt(0)
	v_add_f32_e32 v0, v0, v117
	v_bitop3_b32 v117, v116, 32, v178 bitop3:0x6c
	ds_bpermute_b32 v117, v117, v0
	v_mov_b32_e32 v154, v38
	s_waitcnt lgkmcnt(0)
	v_add_f32_e32 v0, v0, v117
	v_bitop3_b32 v117, v116, 16, v178 bitop3:0x6c
	ds_bpermute_b32 v117, v117, v0
	s_waitcnt lgkmcnt(0)
	v_add_f32_e32 v0, v0, v117
	v_bitop3_b32 v117, v116, 8, v178 bitop3:0x6c
	ds_bpermute_b32 v117, v117, v0
	v_bitop3_b32 v116, v116, 4, v178 bitop3:0x6c
	s_waitcnt lgkmcnt(0)
; DI unsigned pk_bf16(float lo, float hi) { unsigned r; asm("v_cvt_pk_bf16_f32 %0, %1, %2" : "=v"(r) : "v"(lo), "v"(hi)); return r; }
; DI void phase_rowpass(unsigned char* ws, int nrows, const float* xin_lat, const float* xin_ctx, const float* y, const float* gate_base  ,
;                       const float* gpost, bool write_x, bool write_h, const float* hmod_base  , int sc_which, int sh_which, const float* gpre) {
;     ...
;     for (; r < rend; ++r) {
;         const int mi = r < ML ? (r >> 12) : 8;
;         const int rn = r + 1;
;         if (rn < rend) {
;             const float* xi = rn < ML ? xin_lat + (size_t)rn * 1024 : xin_ctx + (size_t)(rn - ML) * 1024;
; #pragma unroll
;             for (int i = 0; i < 4; ++i) xnx[i] = __builtin_nontemporal_load((const f32x4*)(xi + i * 256 + lane * 4));
;             if (y) {
; #pragma unroll
;                 for (int i = 0; i < 4; ++i) ynx[i] = __builtin_nontemporal_load((const f32x4*)(y + (size_t)rn * 1024 + i * 256 + lane * 4));
;             }
;     ...
;         if (write_h) {
;             float ss = 0.f;
; #pragma unroll
;             for (int i = 0; i < 4; ++i) ss += xv[i][0] * xv[i][0] + xv[i][1] * xv[i][1] + xv[i][2] * xv[i][2] + xv[i][3] * xv[i][3];
;             ss = wave_sum(ss);
;             const float rs = rsqrtf(ss * (1.f / 1024.f) + eps);
; #pragma unroll
;             for (int i = 0; i < 4; ++i) {
;                 float hv[4];
; #pragma unroll
;                 for (int j = 0; j < 4; ++j) hv[j] = (xv[i][j] * rs * vpre[i][j]) * (1.f + vsc[i][j]) + vsh[i][j];
;                 u32x2 o; o[0] = pk_bf16(hv[0], hv[1]); o[1] = pk_bf16(hv[2], hv[3]);
;                 *(u32x2*)(H + (size_t)r * 1024 + i * 256 + lane * 4) = o;
;             }
;         }
; #pragma unroll
;         for (int i = 0; i < 4; ++i) { xv[i] = xnx[i]; yv[i] = ynx[i]; }
	v_add_f32_e32 v0, v0, v117
	ds_bpermute_b32 v116, v116, v0
	s_waitcnt lgkmcnt(0)
	v_add_f32_e32 v0, v0, v116
	v_fmamk_f32 v0, v0, 0x3a800000, v141
	v_cmp_gt_f32_e32 vcc, s60, v0
	v_mul_f32_e32 v116, 0x4b800000, v0
	s_nop 0
	v_cndmask_b32_e32 v0, v0, v116, vcc
	v_rsq_f32_e32 v0, v0
	s_nop 0
	v_mul_f32_e32 v116, 0x45800000, v0
	v_cndmask_b32_e32 v0, v0, v116, vcc
	v_mul_f32_e32 v118, v124, v0
	v_mul_f32_e32 v118, v20, v118
	v_fma_f32 v118, v119, v118, v104
	v_mul_f32_e32 v119, v128, v0
	v_mul_f32_e32 v119, v21, v119
	v_add_f32_e32 v124, 1.0, v89
	v_fma_f32 v119, v124, v119, v105
	v_mul_f32_e32 v124, v126, v0
	v_mul_f32_e32 v124, v22, v124
	v_add_f32_e32 v126, 1.0, v90
	v_lshlrev_b64 v[116:117], 11, v[144:145]
	v_fma_f32 v124, v126, v124, v106
	v_mul_f32_e32 v126, v130, v0
	v_lshl_add_u64 v[116:117], v[150:151], 0, v[116:117]
	v_mul_f32_e32 v126, v23, v126
	v_add_f32_e32 v128, 1.0, v91
	v_cvt_pk_bf16_f32 v118, v118, v119
	v_fma_f32 v126, v128, v126, v107
	v_cvt_pk_bf16_f32 v119, v124, v126
	flat_store_dwordx2 v[116:117], v[118:119]
	v_mul_f32_e32 v118, v125, v0
	v_mul_f32_e32 v118, v24, v118
	v_add_f32_e32 v119, 1.0, v84
	v_fma_f32 v118, v119, v118, v100
	v_mul_f32_e32 v119, v129, v0
	v_mul_f32_e32 v119, v25, v119
	v_add_f32_e32 v124, 1.0, v85
	v_fma_f32 v119, v124, v119, v101
	v_mul_f32_e32 v124, v127, v0
	v_mul_f32_e32 v124, v26, v124
	v_add_f32_e32 v125, 1.0, v86
	v_fma_f32 v124, v125, v124, v102
	v_mul_f32_e32 v125, v131, v0
	v_mul_f32_e32 v125, v27, v125
	v_add_f32_e32 v126, 1.0, v87
	v_cvt_pk_bf16_f32 v118, v118, v119
	v_fma_f32 v125, v126, v125, v103
	v_cvt_pk_bf16_f32 v119, v124, v125
	flat_store_dwordx2 v[116:117], v[118:119] offset:512
	v_mul_f32_e32 v118, v133, v0
	v_mul_f32_e32 v118, v28, v118
	v_add_f32_e32 v119, 1.0, v96
	v_fma_f32 v118, v119, v118, v112
	v_mul_f32_e32 v119, v121, v0
	v_mul_f32_e32 v119, v29, v119
	v_add_f32_e32 v121, 1.0, v97
	v_fma_f32 v119, v121, v119, v113
	v_mul_f32_e32 v121, v135, v0
	v_mul_f32_e32 v121, v30, v121
	v_add_f32_e32 v124, 1.0, v98
	v_mul_f32_e32 v123, v123, v0
	v_fma_f32 v121, v124, v121, v114
	v_mul_f32_e32 v123, v31, v123
	v_add_f32_e32 v124, 1.0, v99
	v_cvt_pk_bf16_f32 v118, v118, v119
	v_fma_f32 v123, v124, v123, v115
	v_cvt_pk_bf16_f32 v119, v121, v123
	flat_store_dwordx2 v[116:117], v[118:119] offset:1024
	v_mul_f32_e32 v118, v132, v0
	v_mul_f32_e32 v118, v32, v118
	v_add_f32_e32 v119, 1.0, v92
	v_fma_f32 v118, v119, v118, v108
	v_mul_f32_e32 v119, v120, v0
	v_mul_f32_e32 v119, v33, v119
	v_add_f32_e32 v120, 1.0, v93
	v_fma_f32 v119, v120, v119, v109
	v_mul_f32_e32 v120, v134, v0
	v_mul_f32_e32 v120, v34, v120
	v_add_f32_e32 v121, 1.0, v94
	v_mul_f32_e32 v0, v122, v0
	v_fma_f32 v120, v121, v120, v110
	v_mul_f32_e32 v0, v35, v0
	v_add_f32_e32 v121, 1.0, v95
	v_fma_f32 v0, v121, v0, v111
	v_cvt_pk_bf16_f32 v118, v118, v119
	v_cvt_pk_bf16_f32 v119, v120, v0
	flat_store_dwordx2 v[116:117], v[118:119] offset:1536
	v_mov_b64_e32 v[118:119], v[66:67]
	v_mov_b64_e32 v[130:131], v[70:71]
	v_mov_b64_e32 v[134:135], v[74:75]
	v_mov_b64_e32 v[144:145], v[12:13]
	v_mov_b64_e32 v[116:117], v[64:65]
	v_mov_b64_e32 v[128:129], v[68:69]
	v_mov_b64_e32 v[132:133], v[72:73]
	v_mov_b32_e32 v124, v48
	v_mov_b32_e32 v126, v50
	v_mov_b32_e32 v125, v44
	v_mov_b32_e32 v127, v46
	v_mov_b32_e32 v121, v41
	v_mov_b32_e32 v123, v43
	v_mov_b32_e32 v120, v37
	v_mov_b32_e32 v122, v39
	s_andn2_b64 exec, exec, s[44:45]
	s_cbranch_execz .LBB0_113
.LBB0_105:
	v_lshl_add_u64 v[12:13], v[144:145], 0, s[82:83]
	v_cmp_lt_i32_e32 vcc, v12, v164
	v_cmp_ge_i32_e64 s[40:41], v12, v164
	v_lshlrev_b32_e32 v0, 2, v140
	s_and_saveexec_b64 s[46:47], vcc
	s_cbranch_execz .LBB0_107
	v_add_u32_e32 v36, 0xffff8080, v144
	v_cmp_gt_i32_e32 vcc, 0x7f80, v144
	v_mov_b32_e32 v38, s17
	v_mov_b32_e32 v39, s15
	v_cndmask_b32_e32 v37, 0, v13, vcc
	v_cndmask_b32_e32 v36, v36, v12, vcc
	v_cndmask_b32_e32 v39, v38, v39, vcc
	v_mov_b32_e32 v38, s16
	v_mov_b32_e32 v40, s14
	v_cndmask_b32_e32 v38, v38, v40, vcc
	v_lshlrev_b64 v[36:37], 12, v[36:37]
	v_lshl_add_u64 v[60:61], v[152:153], 0, v[142:143]
	v_lshl_add_u64 v[36:37], v[38:39], 0, v[36:37]
	v_add_co_u32_e32 v60, vcc, 0xb162000, v60
	v_lshl_add_u64 v[36:37], v[36:37], 0, v[0:1]
	s_nop 0
	v_addc_co_u32_e32 v61, vcc, 0, v61, vcc
	flat_load_dwordx4 v[48:51], v[36:37] nt
	flat_load_dwordx4 v[44:47], v[36:37] offset:1024 nt
	flat_load_dwordx4 v[40:43], v[36:37] offset:2048 nt
	s_nop 0
	flat_load_dwordx4 v[36:39], v[36:37] offset:3072 nt
	s_nop 0
	flat_load_dwordx4 v[72:75], v[60:61] nt
	flat_load_dwordx4 v[68:71], v[60:61] offset:1024 nt
	flat_load_dwordx4 v[64:67], v[60:61] offset:2048 nt
	s_nop 0
	flat_load_dwordx4 v[60:63], v[60:61] offset:3072 nt

; DI int obid() { int t = blockIdx.x; asm volatile("" : "+s"(t)); return t; }
; DI int ogrid() { int t = gridDim.x; asm volatile("" : "+s"(t)); return t; }
; DI void phase_rowpass(unsigned char* ws, int nrows, const float* xin_lat, const float* xin_ctx, const float* y, const float* gate_base  ,
;                       const float* gpost, bool write_x, bool write_h, const float* hmod_base  , int sc_which, int sh_which, const float* gpre) {
;     ...
;     const int nwv = ogrid() * 8, per = (nrows + nwv - 1) / nwv;
;     int r = (obid() * 8 + wave) * per;
;     const int rend = min(r + per, nrows);
;     f32x4 xv[4], yv[4], xnx[4], ynx[4];
;     f32x4 vgt[4], vgp[4], vpre[4], vsc[4], vsh[4];
; #pragma unroll
;     for (int i = 0; i < 4; ++i) { xv[i] = (f32x4){0.f, 0.f, 0.f, 0.f}; yv[i] = xv[i]; xnx[i] = xv[i]; ynx[i] = xv[i]; vgt[i] = xv[i]; vgp[i] = xv[i]; vpre[i] = xv[i]; vsc[i] = xv[i]; vsh[i] = xv[i]; }
;     if (r < rend) {
;         const float* xi = r < ML ? xin_lat + (size_t)r * 1024 : xin_ctx + (size_t)(r - ML) * 1024;
; #pragma unroll
;         for (int i = 0; i < 4; ++i) xv[i] = __builtin_nontemporal_load((const f32x4*)(xi + i * 256 + lane * 4));
;         if (y) {
; #pragma unroll
;             for (int i = 0; i < 4; ++i) yv[i] = __builtin_nontemporal_load((const f32x4*)(y + (size_t)r * 1024 + i * 256 + lane * 4));
;         }
; #pragma unroll
;         for (int i = 0; i < 4; ++i) { if (y) vgp[i] = *(const f32x4*)(gpost + i * 256 + lane * 4); if (write_h) vpre[i] = *(const f32x4*)(gpre + i * 256 + lane * 4); }
;     }
.LBB0_143:
	v_mov_b32_e32 v40, v176
	v_mov_b32_e32 v0, v176
	v_mov_b32_e32 v164, 0x358637bd
	s_mov_b32 s2, s66
	s_load_dwordx2 s[14:15], s[0:1], 0xc8
	s_load_dwordx2 s[40:41], s[0:1], 0x48
	s_load_dwordx2 s[42:43], s[0:1], 0x30
	s_load_dwordx2 s[18:19], s[0:1], 0xc8
	s_lshl_b32 s2, s2, 3
	s_abs_i32 s3, s2
	v_cvt_f32_u32_e32 v2, s3
	s_sub_i32 s5, 0, s3
	s_add_i32 s4, s9, s2
	s_add_i32 s4, s4, -1
	v_rcp_iflag_f32_e32 v2, v2
	s_xor_b32 s2, s4, s2
	s_abs_i32 s4, s4
	s_ashr_i32 s2, s2, 31
	v_mul_f32_e32 v2, 0x4f7ffffe, v2
	v_cvt_u32_f32_e32 v2, v2
	v_ashrrev_i32_e32 v0, 6, v0
	v_readfirstlane_b32 s6, v2
	s_mul_i32 s5, s5, s6
	s_mul_hi_u32 s5, s6, s5
	s_add_i32 s6, s6, s5
	s_mul_hi_u32 s5, s4, s6
	s_mul_i32 s6, s5, s3
	s_sub_i32 s4, s4, s6
	s_add_i32 s6, s5, 1
	s_sub_i32 s7, s4, s3
	s_cmp_ge_u32 s4, s3
	s_cselect_b32 s5, s6, s5
	s_cselect_b32 s4, s7, s4
	s_add_i32 s6, s5, 1
	s_cmp_ge_u32 s4, s3
	s_cselect_b32 s3, s6, s5
	s_xor_b32 s3, s3, s2
	s_sub_i32 s2, s3, s2
	s_mov_b32 s3, s33
	s_nop 0
	v_lshl_add_u32 v0, s3, 3, v0
	v_lshrrev_b32_e32 v34, 7, v0
	v_and_b32_e32 v0, 0x7f, v0
	s_lshl_b32 s3, s2, 7
	v_mul_lo_u32 v34, v34, s3
	s_add_i32 s3, s3, 0xffffff81
	v_add_u32_e32 v34, v34, v0
	v_add_u32_e32 v0, s3, v34
	v_min_i32_e32 v165, s9, v0
	v_cmp_lt_i32_e32 vcc, v34, v165
	s_and_saveexec_b64 s[16:17], vcc
	s_cbranch_execz .LBB0_170
	v_readlane_b32 s2, v255, 3
	v_readlane_b32 s3, v255, 4
	s_lshl_b32 s2, s2, 10
	v_readlane_b32 s4, v254, 57
	v_add_u32_e32 v0, 0xffff8000, v34
	v_cmp_gt_i32_e32 vcc, s63, v34
	s_add_i32 s3, s2, 0x400
	v_readlane_b32 s5, v254, 58
	v_cndmask_b32_e32 v2, v0, v34, vcc
	v_mov_b32_e32 v0, s85
	s_waitcnt lgkmcnt(0)
	v_mov_b32_e32 v4, s15
	s_and_b64 s[4:5], s[4:5], exec
	v_ashrrev_i32_e32 v35, 31, v34
	v_cndmask_b32_e32 v5, v0, v4, vcc
	v_mov_b32_e32 v0, s84
	v_mov_b32_e32 v4, s14
	s_cselect_b32 s72, 0, s3
	v_cndmask_b32_e32 v3, 0, v35, vcc
	v_cndmask_b32_e32 v4, v0, v4, vcc
	v_lshlrev_b32_e32 v0, 2, v40
	s_lshl_b64 s[4:5], s[72:73], 2
	v_lshlrev_b64 v[2:3], 12, v[2:3]
	v_and_b32_e32 v0, 0xfc, v0
	s_add_u32 s4, s42, s4
	s_mov_b32 s3, s73
	v_lshl_add_u64 v[2:3], v[4:5], 0, v[2:3]
	v_lshlrev_b32_e32 v0, 2, v0
	s_addc_u32 s5, s43, s5
	s_lshl_b64 s[2:3], s[2:3], 2
	v_lshl_add_u64 v[2:3], v[2:3], 0, v[0:1]
	v_lshlrev_b64 v[36:37], 12, v[34:35]
	s_add_u32 s42, s40, s2
	flat_load_dwordx4 v[130:133], v[2:3] nt
	flat_load_dwordx4 v[142:145], v[2:3] offset:1024 nt
	flat_load_dwordx4 v[118:121], v[2:3] offset:2048 nt
	flat_load_dwordx4 v[138:141], v[2:3] offset:3072 nt
	v_lshl_add_u64 v[2:3], s[84:85], 0, v[36:37]
	s_addc_u32 s43, s41, s3
	v_lshl_add_u64 v[2:3], v[2:3], 0, v[0:1]
	s_mov_b64 s[2:3], 0x16be2000
	v_lshl_add_u64 v[4:5], v[2:3], 0, s[2:3]
	v_add_co_u32_e32 v2, vcc, 0x16be2000, v2
	v_cndmask_b32_e64 v7, 0, 1, s[48:49]
	s_nop 0
	v_addc_co_u32_e32 v3, vcc, 0, v3, vcc
	flat_load_dwordx4 v[122:125], v[4:5] offset:1024 nt
	flat_load_dwordx4 v[114:117], v[4:5] offset:2048 nt
	flat_load_dwordx4 v[126:129], v[2:3] nt
	flat_load_dwordx4 v[134:137], v[4:5] offset:3072 nt
	s_nop 0
	global_load_dwordx4 v[2:5], v0, s[42:43]
	v_lshl_add_u64 v[38:39], s[4:5], 0, v[0:1]
	v_mov_b32_e32 v6, 0
	v_cmp_ne_u32_e64 s[40:41], 1, v7
	s_andn2_b64 vcc, exec, s[48:49]
	v_mov_b32_e32 v10, 0
	v_mov_b32_e32 v11, 0
	v_mov_b32_e32 v12, 0
	v_mov_b32_e32 v13, 0
	s_cbranch_vccnz .LBB0_146
	global_load_dwordx4 v[10:13], v[38:39], off

; DI void phase_rowpass(unsigned char* ws, int nrows, const float* xin_lat, const float* xin_ctx, const float* y, const float* gate_base  ,
;                       const float* gpost, bool write_x, bool write_h, const float* hmod_base  , int sc_which, int sh_which, const float* gpre) {
;     ...
;     int mi_cur = -1;
; #pragma unroll 1
;     for (; r < rend; ++r) {
;         const int mi = r < ML ? (r >> 12) : 8;
;         const int rn = r + 1;
;         if (rn < rend) {
;             const float* xi = rn < ML ? xin_lat + (size_t)rn * 1024 : xin_ctx + (size_t)(rn - ML) * 1024;
; #pragma unroll
;             for (int i = 0; i < 4; ++i) xnx[i] = __builtin_nontemporal_load((const f32x4*)(xi + i * 256 + lane * 4));
;             if (y) {
; #pragma unroll
;                 for (int i = 0; i < 4; ++i) ynx[i] = __builtin_nontemporal_load((const f32x4*)(y + (size_t)rn * 1024 + i * 256 + lane * 4));
;             }
;         }
.LBB0_152:
	v_add_u32_e32 v156, 0x80, v34
	v_lshl_add_u64 v[38:39], s[10:11], 0, v[0:1]
	s_mov_b64 s[2:3], 0x5000
	v_ashrrev_i32_e32 v157, 31, v156
	v_lshl_add_u64 v[146:147], v[38:39], 0, s[2:3]
	s_mov_b64 s[2:3], 0x36000
	v_lshl_add_u64 v[152:153], s[18:19], 0, v[36:37]
	v_lshlrev_b64 v[154:155], 11, v[34:35]
	v_and_b32_e32 v35, 63, v40
	v_lshlrev_b64 v[158:159], 12, v[156:157]
	v_mov_b32_e32 v36, v1
	v_mov_b32_e32 v37, v1
	v_lshl_add_u64 v[148:149], v[38:39], 0, s[2:3]
	s_waitcnt vmcnt(0)
	v_mov_b32_e32 v150, v33
	v_mov_b32_e32 v33, v20
	v_mov_b32_e32 v20, v30
	v_mov_b32_e32 v30, v5
	v_mov_b32_e32 v5, v16
	v_mov_b32_e32 v16, v2
	v_mov_b32_e32 v2, v34
	v_lshl_or_b32 v154, v35, 3, v154
	v_lshl_or_b32 v158, v35, 4, v158
	v_mov_b32_e32 v34, v1
	v_mov_b32_e32 v35, v1
	v_mov_b64_e32 v[52:53], v[36:37]
	v_mov_b64_e32 v[56:57], v[36:37]
	v_mov_b64_e32 v[60:61], v[36:37]
	v_mov_b64_e32 v[88:89], v[36:37]
	v_mov_b64_e32 v[92:93], v[36:37]
	v_mov_b64_e32 v[96:97], v[36:37]
	v_mov_b64_e32 v[100:101], v[36:37]
	v_mov_b64_e32 v[112:113], v[36:37]
	v_mov_b64_e32 v[108:109], v[36:37]
	v_mov_b64_e32 v[104:105], v[36:37]
	v_mov_b64_e32 v[84:85], v[36:37]
	v_mov_b64_e32 v[40:41], v[36:37]
	v_mov_b64_e32 v[44:45], v[36:37]
	v_mov_b64_e32 v[48:49], v[36:37]
	v_mov_b64_e32 v[64:65], v[36:37]
	v_mov_b64_e32 v[68:69], v[36:37]
	v_mov_b64_e32 v[72:73], v[36:37]
	v_mov_b64_e32 v[76:77], v[36:37]
	v_mov_b64_e32 v[80:81], v[36:37]
	v_mov_b32_e32 v151, v21
	v_mov_b32_e32 v21, v18
	v_mov_b32_e32 v18, v31
	v_mov_b32_e32 v31, v17
	v_mov_b32_e32 v17, v14
	v_mov_b32_e32 v14, v3
	v_mov_b32_e32 v3, v1
	v_mov_b32_e32 v166, -1
	s_mov_b64 s[8:9], 0
	s_mov_b64 s[10:11], 0
	v_mov_b64_e32 v[50:51], v[34:35]
	v_mov_b64_e32 v[54:55], v[34:35]
	v_mov_b64_e32 v[58:59], v[34:35]
	v_mov_b64_e32 v[86:87], v[34:35]
	v_mov_b64_e32 v[90:91], v[34:35]
	v_mov_b64_e32 v[94:95], v[34:35]
	v_mov_b64_e32 v[98:99], v[34:35]
	v_mov_b64_e32 v[110:111], v[34:35]
	v_mov_b64_e32 v[106:107], v[34:35]
	v_mov_b64_e32 v[102:103], v[34:35]
	v_mov_b64_e32 v[82:83], v[34:35]
	v_mov_b64_e32 v[38:39], v[34:35]
	v_mov_b64_e32 v[42:43], v[34:35]
	v_mov_b64_e32 v[46:47], v[34:35]
	v_mov_b64_e32 v[62:63], v[34:35]
	v_mov_b64_e32 v[66:67], v[34:35]
	v_mov_b64_e32 v[70:71], v[34:35]
	v_mov_b64_e32 v[74:75], v[34:35]
	v_mov_b64_e32 v[78:79], v[34:35]
	s_waitcnt lgkmcnt(0)
	v_mov_b32_e32 v162, v131
	v_mov_b32_e32 v160, v133
	v_mov_b32_e32 v131, v142
	v_mov_b32_e32 v163, v143
	v_mov_b32_e32 v133, v144
	v_mov_b32_e32 v161, v145
	v_mov_b32_e32 v145, v118
	v_mov_b32_e32 v143, v120
	v_mov_b32_e32 v144, v138
	v_mov_b32_e32 v118, v139
	v_mov_b32_e32 v142, v140
	v_mov_b32_e32 v120, v141
	s_branch .LBB0_154
.LBB0_153:
	s_add_u32 s10, s10, 0x80
	v_add_u32_e32 v114, s10, v2
	s_addc_u32 s11, s11, 0
	s_mov_b64 s[4:5], 0x80000
	s_mov_b64 s[2:3], 0x40000
	v_cmp_ge_i32_e32 vcc, v114, v165
	v_mov_b64_e32 v[136:137], v[88:89]
	v_mov_b64_e32 v[116:117], v[92:93]
	v_mov_b64_e32 v[124:125], v[96:97]
	v_mov_b64_e32 v[128:129], v[100:101]
	v_lshl_add_u64 v[152:153], v[152:153], 0, s[4:5]
	v_lshl_add_u64 v[154:155], v[154:155], 0, s[2:3]
	v_lshl_add_u64 v[158:159], v[158:159], 0, s[4:5]
	s_or_b64 s[8:9], vcc, s[8:9]
	v_mov_b64_e32 v[134:135], v[86:87]
	v_mov_b64_e32 v[114:115], v[90:91]
	v_mov_b64_e32 v[122:123], v[94:95]
	v_mov_b64_e32 v[126:127], v[98:99]
	v_mov_b32_e32 v130, v58
	v_mov_b32_e32 v162, v59
	v_mov_b32_e32 v132, v60
	v_mov_b32_e32 v160, v61
	v_mov_b32_e32 v131, v54
	v_mov_b32_e32 v163, v55
	v_mov_b32_e32 v133, v56
	v_mov_b32_e32 v161, v57
	v_mov_b32_e32 v145, v50
	v_mov_b32_e32 v119, v51
	v_mov_b32_e32 v143, v52
	v_mov_b32_e32 v121, v53
	v_mov_b32_e32 v144, v34
	v_mov_b32_e32 v118, v35
	v_mov_b32_e32 v142, v36
	v_mov_b32_e32 v120, v37
	s_andn2_b64 exec, exec, s[8:9]
	s_cbranch_execz .LBB0_170
.LBB0_154:
	v_lshl_add_u64 v[138:139], v[2:3], 0, s[10:11]
	v_add_u32_e32 v139, 0x80, v138
	v_cmp_lt_i32_e32 vcc, v139, v165
	s_and_saveexec_b64 s[18:19], vcc
	s_cbranch_execz .LBB0_156
	v_add_u32_e32 v36, 0xffff8080, v138
	v_lshl_add_u64 v[34:35], v[156:157], 0, s[10:11]
	v_cmp_gt_i32_e32 vcc, 0x7f80, v138
	v_mov_b32_e32 v37, s15
	v_mov_b32_e32 v50, s14
	v_cndmask_b32_e32 v34, v36, v34, vcc
	v_mov_b32_e32 v36, s85
	v_cndmask_b32_e32 v35, 0, v35, vcc
	v_cndmask_b32_e32 v37, v36, v37, vcc
	v_mov_b32_e32 v36, s84
	v_cndmask_b32_e32 v36, v36, v50, vcc
	v_lshlrev_b64 v[34:35], 12, v[34:35]
	v_lshl_add_u64 v[86:87], s[84:85], 0, v[158:159]
	v_lshl_add_u64 v[34:35], v[36:37], 0, v[34:35]
	v_add_co_u32_e32 v86, vcc, 0x16be2000, v86
	v_lshl_add_u64 v[34:35], v[34:35], 0, v[0:1]
	s_nop 0
	v_addc_co_u32_e32 v87, vcc, 0, v87, vcc
	flat_load_dwordx4 v[58:61], v[34:35] nt
	flat_load_dwordx4 v[54:57], v[34:35] offset:1024 nt
	flat_load_dwordx4 v[50:53], v[34:35] offset:2048 nt
	s_nop 0
	flat_load_dwordx4 v[34:37], v[34:35] offset:3072 nt
	s_nop 0
	flat_load_dwordx4 v[98:101], v[86:87] nt
	flat_load_dwordx4 v[94:97], v[86:87] offset:1024 nt
	flat_load_dwordx4 v[90:93], v[86:87] offset:2048 nt
	s_nop 0
	flat_load_dwordx4 v[86:89], v[86:87] offset:3072 nt
